# attention: the 16 v_exp of the first inter-barrier block moved into the second-half QK^T MFMA gaps (fmamk writes the exp destination, exp in place later, 1 wait state kept before consumers)
# speedup vs baseline: 1.0064x; 1.0022x over previous
.LBB0_565:
	v_cndmask_b32_e64 v153, v148, v209, s[6:7]
	v_mul_f32_e32 v144, 0xbdd53b94, v153
	v_fmamk_f32 v141, v80, 0x3dd53b94, v144
	v_fmamk_f32 v143, v81, 0x3dd53b94, v144
	v_fmamk_f32 v139, v82, 0x3dd53b94, v144
	v_fmamk_f32 v142, v83, 0x3dd53b94, v144
	v_fmamk_f32 v138, v84, 0x3dd53b94, v144
	v_fmamk_f32 v140, v85, 0x3dd53b94, v144
	v_fmamk_f32 v136, v86, 0x3dd53b94, v144
	v_fmamk_f32 v137, v87, 0x3dd53b94, v144
	v_fmamk_f32 v133, v88, 0x3dd53b94, v144
	v_fmamk_f32 v135, v89, 0x3dd53b94, v144
	v_fmamk_f32 v132, v90, 0x3dd53b94, v144
	v_fmamk_f32 v134, v91, 0x3dd53b94, v144
	v_fmamk_f32 v129, v92, 0x3dd53b94, v144
	v_fmamk_f32 v131, v93, 0x3dd53b94, v144
	v_fmamk_f32 v128, v94, 0x3dd53b94, v144
	v_fmamk_f32 v130, v95, 0x3dd53b94, v144
	v_fmamk_f32 v218, v68, 0x3dd53b94, v144
	v_fmamk_f32 v148, v71, 0x3dd53b94, v144
	v_fmamk_f32 v149, v72, 0x3dd53b94, v144
	v_fmamk_f32 v219, v77, 0x3dd53b94, v144
	v_fmamk_f32 v155, v64, 0x3dd53b94, v144
	v_fmamk_f32 v209, v65, 0x3dd53b94, v144
	v_fmamk_f32 v216, v66, 0x3dd53b94, v144
	v_fmamk_f32 v217, v67, 0x3dd53b94, v144
	v_fmamk_f32 v146, v69, 0x3dd53b94, v144
	v_fmamk_f32 v147, v70, 0x3dd53b94, v144
	v_fmamk_f32 v150, v73, 0x3dd53b94, v144
	v_fmamk_f32 v151, v74, 0x3dd53b94, v144
	v_fmamk_f32 v154, v75, 0x3dd53b94, v144
	v_fmamk_f32 v145, v76, 0x3dd53b94, v144
	v_fmamk_f32 v220, v78, 0x3dd53b94, v144
	v_fmac_f32_e32 v144, 0x3dd53b94, v79
	s_waitcnt lgkmcnt(0)
	s_barrier
	ds_read_b128 v[64:67], v189 offset:32768
	ds_read_b128 v[68:71], v189 offset:40960
	ds_read_b128 v[222:225], v190 offset:32768
	ds_read_b128 v[226:229], v190 offset:40960
	v_exp_f32_e32 v155, v155
	v_exp_f32_e32 v209, v209
	s_waitcnt lgkmcnt(3)
	v_mfma_f32_32x32x16_bf16 v[80:95], v[64:67], v[120:123], 0
	v_exp_f32_e32 v216, v216
	v_exp_f32_e32 v217, v217
	s_waitcnt lgkmcnt(2)
	v_mfma_f32_32x32x16_bf16 v[64:79], v[68:71], v[120:123], 0
	v_exp_f32_e32 v141, v141
	v_exp_f32_e32 v143, v143
	v_add_f32_e32 v240, 0, v141
	v_exp_f32_e32 v139, v139
	v_add_f32_e32 v240, v143, v240
	s_waitcnt lgkmcnt(0)
	v_mfma_f32_32x32x16_bf16 v[64:79], v[226:229], v[124:127], v[64:79]
	v_exp_f32_e32 v142, v142
	v_add_f32_e32 v240, v139, v240
	v_exp_f32_e32 v138, v138
	v_add_f32_e32 v240, v142, v240
	v_mfma_f32_32x32x16_bf16 v[80:95], v[222:225], v[124:127], v[80:95]
	v_exp_f32_e32 v146, v146
	v_exp_f32_e32 v140, v140
	v_add_f32_e32 v240, v138, v240
	ds_read_b128 v[222:225], v191 offset:32768
	ds_read_b128 v[226:229], v191 offset:40960
	s_waitcnt lgkmcnt(0)
	v_mfma_f32_32x32x16_bf16 v[64:79], v[226:229], v[116:119], v[64:79]
	v_exp_f32_e32 v136, v136
	v_add_f32_e32 v240, v140, v240
	v_exp_f32_e32 v147, v147
	v_mfma_f32_32x32x16_bf16 v[80:95], v[222:225], v[116:119], v[80:95]
	v_exp_f32_e32 v137, v137
	v_add_f32_e32 v240, v136, v240
	v_exp_f32_e32 v133, v133
	v_add_f32_e32 v240, v137, v240
	ds_read_b128 v[222:225], v192 offset:32768
	ds_read_b128 v[226:229], v192 offset:40960
	s_waitcnt lgkmcnt(0)
	v_mfma_f32_32x32x16_bf16 v[64:79], v[226:229], v[112:115], v[64:79]
	v_exp_f32_e32 v154, v154
	v_exp_f32_e32 v135, v135
	v_add_f32_e32 v240, v133, v240
	v_mfma_f32_32x32x16_bf16 v[80:95], v[222:225], v[112:115], v[80:95]
	v_exp_f32_e32 v132, v132
	v_add_f32_e32 v240, v135, v240
	v_exp_f32_e32 v145, v145
	ds_read_b128 v[222:225], v193 offset:32768
	ds_read_b128 v[226:229], v193 offset:40960
	s_waitcnt lgkmcnt(0)
	v_mfma_f32_32x32x16_bf16 v[64:79], v[226:229], v[108:111], v[64:79]
	v_exp_f32_e32 v134, v134
	v_add_f32_e32 v240, v132, v240
	v_exp_f32_e32 v129, v129
	v_add_f32_e32 v240, v134, v240
	v_mfma_f32_32x32x16_bf16 v[80:95], v[222:225], v[108:111], v[80:95]
	v_exp_f32_e32 v144, v144
	v_exp_f32_e32 v131, v131
	v_add_f32_e32 v240, v129, v240
	ds_read_b128 v[222:225], v194 offset:32768
	ds_read_b128 v[226:229], v194 offset:40960
	s_waitcnt lgkmcnt(0)
	v_mfma_f32_32x32x16_bf16 v[64:79], v[226:229], v[104:107], v[64:79]
	v_exp_f32_e32 v128, v128
	v_add_f32_e32 v240, v131, v240
	v_exp_f32_e32 v218, v218
	v_mfma_f32_32x32x16_bf16 v[80:95], v[222:225], v[104:107], v[80:95]
	v_exp_f32_e32 v130, v130
	v_add_f32_e32 v240, v128, v240
	v_add_f32_e32 v240, v130, v240
	ds_read_b128 v[222:225], v195 offset:32768
	ds_read_b128 v[226:229], v195 offset:40960
	s_waitcnt lgkmcnt(0)
	v_mfma_f32_32x32x16_bf16 v[64:79], v[226:229], v[100:103], v[64:79]
	v_exp_f32_e32 v148, v148
	v_add_f32_e32 v240, v155, v240
	v_mfma_f32_32x32x16_bf16 v[80:95], v[222:225], v[100:103], v[80:95]
	v_add_f32_e32 v240, v209, v240
	v_exp_f32_e32 v149, v149
	ds_read_b128 v[222:225], v196 offset:32768
	ds_read_b128 v[226:229], v196 offset:40960
	s_waitcnt lgkmcnt(0)
	v_mfma_f32_32x32x16_bf16 v[64:79], v[226:229], v[96:99], v[64:79]
	v_add_f32_e32 v240, v216, v240
	v_add_f32_e32 v240, v217, v240
	v_mfma_f32_32x32x16_bf16 v[80:95], v[222:225], v[96:99], v[80:95]
	v_exp_f32_e32 v150, v150
	v_add_f32_e32 v240, v218, v240
	ds_read_b128 v[222:225], v199
	ds_read_b128 v[226:229], v199 offset:4096
	ds_read_b128 v[230:233], v197
	s_waitcnt lgkmcnt(0)
	v_mfma_f32_32x32x16_bf16 v[64:79], v[226:229], v[230:233], v[64:79]
	v_add_f32_e32 v240, v146, v240
	v_exp_f32_e32 v151, v151
	v_mfma_f32_32x32x16_bf16 v[80:95], v[222:225], v[230:233], v[80:95]
	v_add_f32_e32 v240, v147, v240
	v_add_f32_e32 v240, v148, v240
	ds_read_b128 v[222:225], v201
	ds_read_b128 v[226:229], v201 offset:4096
	ds_read_b128 v[230:233], v184
	s_waitcnt lgkmcnt(0)
	v_mfma_f32_32x32x16_bf16 v[64:79], v[226:229], v[230:233], v[64:79]
	v_exp_f32_e32 v219, v219
	v_add_f32_e32 v240, v149, v240
	v_mfma_f32_32x32x16_bf16 v[80:95], v[222:225], v[230:233], v[80:95]
	v_add_f32_e32 v240, v150, v240
	v_exp_f32_e32 v220, v220
	ds_read_b128 v[222:225], v203
	ds_read_b128 v[226:229], v203 offset:4096
	ds_read_b128 v[230:233], v183
	s_waitcnt lgkmcnt(0)
	v_mfma_f32_32x32x16_bf16 v[64:79], v[226:229], v[230:233], v[64:79]
	v_add_f32_e32 v240, v151, v240
	v_add_f32_e32 v240, v154, v240
	v_mfma_f32_32x32x16_bf16 v[80:95], v[222:225], v[230:233], v[80:95]
	v_add_f32_e32 v240, v145, v240
	v_add_f32_e32 v240, v219, v240
	ds_read_b128 v[222:225], v205
	ds_read_b128 v[226:229], v205 offset:4096
	ds_read_b128 v[230:233], v182
	s_waitcnt lgkmcnt(0)
	v_mfma_f32_32x32x16_bf16 v[64:79], v[226:229], v[230:233], v[64:79]
	v_add_f32_e32 v240, v220, v240
	v_add_f32_e32 v240, v144, v240
	v_mfma_f32_32x32x16_bf16 v[80:95], v[222:225], v[230:233], v[80:95]
	v_cvt_pk_bf16_f32 v226, v218, v146
	v_cvt_pk_bf16_f32 v227, v147, v148
	v_cvt_pk_bf16_f32 v228, v149, v150
	v_cvt_pk_bf16_f32 v229, v151, v154
	v_cvt_pk_bf16_f32 v230, v145, v219
	v_cvt_pk_bf16_f32 v231, v220, v144
	v_mov_b32_e32 v218, v240
	v_mov_b32_e32 v219, v240
	v_cvt_pk_bf16_f32 v148, v141, v143
	v_cvt_pk_bf16_f32 v149, v139, v142
	v_cvt_pk_bf16_f32 v150, v138, v140
	v_cvt_pk_bf16_f32 v151, v136, v137
	v_permlane32_swap_b32_e32 v218, v219
	v_permlane32_swap_b32_e32 v148, v150
	v_permlane32_swap_b32_e32 v149, v151
	v_cvt_pk_bf16_f32 v220, v133, v135
	v_cvt_pk_bf16_f32 v221, v132, v134
	v_cvt_pk_bf16_f32 v222, v129, v131
	v_cvt_pk_bf16_f32 v223, v128, v130
	v_cvt_pk_bf16_f32 v224, v155, v209
	v_cvt_pk_bf16_f32 v225, v216, v217
	s_nop 0
	v_permlane32_swap_b32_e32 v220, v222
	v_permlane32_swap_b32_e32 v221, v223
	v_permlane32_swap_b32_e32 v224, v226
	v_permlane32_swap_b32_e32 v225, v227
	v_permlane32_swap_b32_e32 v228, v230
	v_permlane32_swap_b32_e32 v229, v231
	s_mov_b32 s0, 0x34ec0000
	v_add_co_u32_e32 v132, vcc, s0, v172
	s_mov_b32 s0, 0x34ee0000
	s_nop 0
	v_addc_co_u32_e32 v133, vcc, 0, v173, vcc
	v_add_co_u32_e32 v136, vcc, s0, v172
	s_mov_b32 s0, 0x1ea06000
	s_nop 0
	v_addc_co_u32_e32 v137, vcc, 0, v173, vcc
	global_load_dwordx4 v[128:131], v[132:133], off offset:256
	s_nop 0
	v_xor_b32_e32 v134, v243, v132
	v_mov_b32_e32 v135, v133
	s_lshl_b32 s100, s33, 4
	s_add_i32 m0, s100, 0xc000
	s_nop 0
	global_load_lds_dwordx4 v[134:135], off
	s_nop 0
	global_load_dwordx4 v[140:143], v[136:137], off offset:256
	s_nop 0
	v_xor_b32_e32 v138, v243, v136
	v_mov_b32_e32 v139, v137
	s_add_i32 m0, s100, 0xe000
	s_nop 0
	global_load_lds_dwordx4 v[138:139], off
	v_add_co_u32_e32 v144, vcc, s0, v174
	s_nop 1
	v_addc_co_u32_e32 v145, vcc, 0, v175, vcc
	v_xor_b32_e32 v144, v242, v144
	s_add_i32 m0, s100, 0x12000
	s_nop 0
	global_load_lds_dwordx4 v[144:145], off
	ds_read_b64_tr_b16 v[172:173], v180 offset:0
	ds_read_b64_tr_b16 v[174:175], v180 offset:0x800
	ds_read_b64_tr_b16 v[232:233], v180 offset:0x1000
	ds_read_b64_tr_b16 v[234:235], v180 offset:0x1800
	ds_read_b64_tr_b16 v[236:237], v180 offset:0x2000
	ds_read_b64_tr_b16 v[238:239], v180 offset:0x2800
	ds_read_b64_tr_b16 v[248:249], v180 offset:0x3000
	ds_read_b64_tr_b16 v[250:251], v180 offset:0x3800
	s_nop 0
	s_waitcnt lgkmcnt(6)
	v_mfma_f32_32x32x16_bf16 v[0:15], v[148:151], v[172:175], v[0:15]
	ds_read_b64_tr_b16 v[172:173], v180 offset:0x200
	ds_read_b64_tr_b16 v[174:175], v180 offset:0xa00
	s_waitcnt lgkmcnt(6)
	v_mfma_f32_32x32x16_bf16 v[0:15], v[220:223], v[232:235], v[0:15]
	ds_read_b64_tr_b16 v[232:233], v180 offset:0x1200
	ds_read_b64_tr_b16 v[234:235], v180 offset:0x1a00
	s_waitcnt lgkmcnt(6)
	v_mfma_f32_32x32x16_bf16 v[0:15], v[224:227], v[236:239], v[0:15]
	ds_read_b64_tr_b16 v[236:237], v180 offset:0x2200
	ds_read_b64_tr_b16 v[238:239], v180 offset:0x2a00
	s_waitcnt lgkmcnt(6)
	v_mfma_f32_32x32x16_bf16 v[0:15], v[228:231], v[248:251], v[0:15]
	ds_read_b64_tr_b16 v[248:249], v180 offset:0x3200
	ds_read_b64_tr_b16 v[250:251], v180 offset:0x3a00
	s_waitcnt lgkmcnt(6)
	v_mfma_f32_32x32x16_bf16 v[48:63], v[148:151], v[172:175], v[48:63]
	ds_read_b64_tr_b16 v[172:173], v180 offset:0x400
	ds_read_b64_tr_b16 v[174:175], v180 offset:0xc00
	s_waitcnt lgkmcnt(6)
	v_mfma_f32_32x32x16_bf16 v[48:63], v[220:223], v[232:235], v[48:63]
	ds_read_b64_tr_b16 v[232:233], v180 offset:0x1400
	ds_read_b64_tr_b16 v[234:235], v180 offset:0x1c00
	s_waitcnt lgkmcnt(6)
	v_mfma_f32_32x32x16_bf16 v[48:63], v[224:227], v[236:239], v[48:63]
	ds_read_b64_tr_b16 v[236:237], v180 offset:0x2400
	ds_read_b64_tr_b16 v[238:239], v180 offset:0x2c00
	s_waitcnt lgkmcnt(6)
	v_mfma_f32_32x32x16_bf16 v[48:63], v[228:231], v[248:251], v[48:63]
	ds_read_b64_tr_b16 v[248:249], v180 offset:0x3400
	ds_read_b64_tr_b16 v[250:251], v180 offset:0x3c00
	s_waitcnt lgkmcnt(6)
	v_mfma_f32_32x32x16_bf16 v[32:47], v[148:151], v[172:175], v[32:47]
	ds_read_b64_tr_b16 v[172:173], v180 offset:0x600
	ds_read_b64_tr_b16 v[174:175], v180 offset:0xe00
	s_waitcnt lgkmcnt(6)
	v_mfma_f32_32x32x16_bf16 v[32:47], v[220:223], v[232:235], v[32:47]
	ds_read_b64_tr_b16 v[232:233], v180 offset:0x1600
	ds_read_b64_tr_b16 v[234:235], v180 offset:0x1e00
	s_waitcnt lgkmcnt(6)
	v_mfma_f32_32x32x16_bf16 v[32:47], v[224:227], v[236:239], v[32:47]
	ds_read_b64_tr_b16 v[236:237], v180 offset:0x2600
	ds_read_b64_tr_b16 v[238:239], v180 offset:0x2e00
	s_waitcnt lgkmcnt(6)
	v_mfma_f32_32x32x16_bf16 v[32:47], v[228:231], v[248:251], v[32:47]
	ds_read_b64_tr_b16 v[248:249], v180 offset:0x3600
	ds_read_b64_tr_b16 v[250:251], v180 offset:0x3e00
	s_waitcnt lgkmcnt(6)
	v_mfma_f32_32x32x16_bf16 v[16:31], v[148:151], v[172:175], v[16:31]
	v_max_f32_e32 v148, v81, v81
	v_max_f32_e32 v149, v80, v80
	v_max_f32_e32 v148, v149, v148
	v_max3_f32 v148, v148, v82, v83
	v_max3_f32 v148, v148, v84, v85
	v_max3_f32 v148, v148, v86, v87
	v_max3_f32 v148, v148, v88, v89
	v_max3_f32 v148, v148, v90, v91
	v_max3_f32 v148, v148, v92, v93
	s_waitcnt lgkmcnt(4)
	v_mfma_f32_32x32x16_bf16 v[16:31], v[220:223], v[232:235], v[16:31]
	v_max3_f32 v148, v148, v94, v95
	v_max3_f32 v148, v148, v64, v65
	v_max3_f32 v148, v148, v66, v67
	v_max3_f32 v148, v148, v68, v69
	v_max3_f32 v148, v148, v70, v71
	v_max3_f32 v148, v148, v72, v73
	v_max3_f32 v148, v148, v74, v75
	v_max3_f32 v148, v148, v76, v77
	s_waitcnt lgkmcnt(2)
	v_mfma_f32_32x32x16_bf16 v[16:31], v[224:227], v[236:239], v[16:31]
	v_max3_f32 v148, v148, v78, v79
	v_mov_b32_e32 v149, v148
	s_nop 1
	v_permlane32_swap_b32_e32 v148, v149
	v_max_f32_e32 v149, v149, v149
	v_max_f32_e32 v148, v148, v148
	v_max_f32_e32 v148, v148, v149
	v_sub_f32_e32 v149, v148, v153
	v_cmp_ge_f32_e32 vcc, s90, v149
	v_max_f32_e32 v149, v153, v153
	v_max_f32_e32 v149, v149, v148
	s_waitcnt lgkmcnt(0)
	v_mfma_f32_32x32x16_bf16 v[16:31], v[228:231], v[248:251], v[16:31]
	v_sub_f32_e32 v148, v153, v149
	v_mul_f32_e32 v148, 0x3dd53b94, v148
	v_exp_f32_e32 v148, v148
	s_cmp_eq_u64 vcc, exec
	s_cselect_b64 s[6:7], -1, 0
	s_barrier
	s_waitcnt vmcnt(0)
	v_cndmask_b32_e64 v148, v148, 1.0, s[6:7]
	v_cmp_gt_f32_e32 vcc, 1.0, v148
	s_waitcnt vmcnt(4)
	ds_write_b128 v185, v[128:131] offset:16384
	s_waitcnt vmcnt(2)
	ds_write_b128 v186, v[140:143] offset:16384
	s_waitcnt vmcnt(1)
	s_waitcnt vmcnt(0)
	s_cbranch_vccz .LBB0_569
	s_and_saveexec_b64 s[0:1], s[4:5]
	ds_write_b32 v178, v148 offset:128
	s_or_b64 exec, exec, s[0:1]
	s_waitcnt lgkmcnt(0)
	v_add_u32_e32 v140, v157, v160
	ds_read_b128 v[128:131], v140 offset:224
	ds_read_b128 v[132:135], v140 offset:192
	ds_read_b128 v[136:139], v140 offset:160
	ds_read_b128 v[140:143], v140 offset:128
	s_waitcnt lgkmcnt(3)
	v_pk_mul_f32 v[12:13], v[12:13], v[128:129]
	s_waitcnt lgkmcnt(2)
	v_pk_mul_f32 v[8:9], v[8:9], v[132:133]
	s_waitcnt lgkmcnt(1)
	v_pk_mul_f32 v[4:5], v[4:5], v[136:137]
	v_pk_mul_f32 v[14:15], v[14:15], v[130:131]
	v_pk_mul_f32 v[10:11], v[10:11], v[134:135]
	v_pk_mul_f32 v[6:7], v[6:7], v[138:139]
	s_waitcnt lgkmcnt(0)
	v_pk_mul_f32 v[2:3], v[2:3], v[142:143]
	v_pk_mul_f32 v[0:1], v[0:1], v[140:141]
	v_pk_mul_f32 v[60:61], v[60:61], v[128:129]
	v_pk_mul_f32 v[56:57], v[56:57], v[132:133]
	v_pk_mul_f32 v[52:53], v[52:53], v[136:137]
	v_pk_mul_f32 v[62:63], v[62:63], v[130:131]
	v_pk_mul_f32 v[58:59], v[58:59], v[134:135]
	v_pk_mul_f32 v[54:55], v[54:55], v[138:139]
	v_pk_mul_f32 v[50:51], v[50:51], v[142:143]
	v_pk_mul_f32 v[48:49], v[48:49], v[140:141]
	v_pk_mul_f32 v[44:45], v[44:45], v[128:129]
	v_pk_mul_f32 v[40:41], v[40:41], v[132:133]
	v_pk_mul_f32 v[36:37], v[36:37], v[136:137]
	v_pk_mul_f32 v[46:47], v[46:47], v[130:131]
	v_pk_mul_f32 v[42:43], v[42:43], v[134:135]
	v_pk_mul_f32 v[38:39], v[38:39], v[138:139]
	v_pk_mul_f32 v[34:35], v[34:35], v[142:143]
	v_pk_mul_f32 v[32:33], v[32:33], v[140:141]
	v_pk_mul_f32 v[28:29], v[28:29], v[128:129]
	v_pk_mul_f32 v[24:25], v[24:25], v[132:133]
	v_pk_mul_f32 v[20:21], v[20:21], v[136:137]
	v_pk_mul_f32 v[30:31], v[30:31], v[130:131]
	v_pk_mul_f32 v[26:27], v[26:27], v[134:135]
	v_pk_mul_f32 v[22:23], v[22:23], v[138:139]
	v_pk_mul_f32 v[18:19], v[18:19], v[142:143]
	v_pk_mul_f32 v[16:17], v[16:17], v[140:141]
